# P6 mid-K gate-rescale hook and output epilogue regenerated by hand: 16 gate loads in flight with counted vmcnt over the hook's own loads, no canonicalize ops; on top of P7/P9 epilogue rewrites
# baseline (speedup 1.0000x reference)
.LBB0_615:
	v_lshlrev_b32_e32 v232, 10, v180
	v_add_lshl_u32 v232, v232, v182, 1
	v_mov_b32_e32 v233, v232
	global_load_dwordx4 v[134:137], v233, s[10:11]
	global_load_dwordx4 v[138:141], v233, s[10:11] offset:256
	v_add_u32_e32 v233, 0x8000, v232
	global_load_dwordx4 v[142:145], v233, s[10:11]
	global_load_dwordx4 v[146:149], v233, s[10:11] offset:256
	v_add_u32_e32 v233, 0x10000, v232
	global_load_dwordx4 v[150:153], v233, s[10:11]
	global_load_dwordx4 v[154:157], v233, s[10:11] offset:256
	v_add_u32_e32 v233, 0x18000, v232
	global_load_dwordx4 v[158:161], v233, s[10:11]
	global_load_dwordx4 v[192:195], v233, s[10:11] offset:256
	v_add_u32_e32 v233, 0x40000, v232
	global_load_dwordx4 v[196:199], v233, s[10:11]
	global_load_dwordx4 v[200:203], v233, s[10:11] offset:256
	v_add_u32_e32 v233, 0x48000, v232
	global_load_dwordx4 v[204:207], v233, s[10:11]
	global_load_dwordx4 v[208:211], v233, s[10:11] offset:256
	v_add_u32_e32 v233, 0x50000, v232
	global_load_dwordx4 v[212:215], v233, s[10:11]
	global_load_dwordx4 v[216:219], v233, s[10:11] offset:256
	v_add_u32_e32 v233, 0x58000, v232
	global_load_dwordx4 v[220:223], v233, s[10:11]
	global_load_dwordx4 v[224:227], v233, s[10:11] offset:256
	s_and_b64 vcc, exec, s[0:1]
	s_mov_b32 s41, s28
	s_mov_b32 s40, s30
	s_mov_b64 s[42:43], s[36:37]
	s_mov_b64 s[38:39], s[34:35]
	s_waitcnt vmcnt(15)
	v_lshlrev_b32_e32 v248, 16, v134
	v_and_b32_e32 v249, 0xffff0000, v134
	v_lshlrev_b32_e32 v250, 16, v135
	v_and_b32_e32 v251, 0xffff0000, v135
	v_lshlrev_b32_e32 v252, 16, v136
	v_and_b32_e32 v253, 0xffff0000, v136
	v_lshlrev_b32_e32 v254, 16, v137
	v_and_b32_e32 v255, 0xffff0000, v137
	v_pk_mul_f32 v[130:131], v[130:131], v[248:249]
	v_pk_mul_f32 v[132:133], v[132:133], v[250:251]
	v_pk_mul_f32 v[126:127], v[126:127], v[252:253]
	v_pk_mul_f32 v[128:129], v[128:129], v[254:255]
	v_cvt_pk_bf16_f32 v134, v130, v131
	v_cvt_pk_bf16_f32 v135, v132, v133
	v_cvt_pk_bf16_f32 v136, v126, v127
	v_cvt_pk_bf16_f32 v137, v128, v129
	v_mov_b32_e32 v233, v232
	global_store_dwordx4 v233, v[134:137], s[6:7]
	s_waitcnt vmcnt(15)
	v_lshlrev_b32_e32 v248, 16, v138
	v_and_b32_e32 v249, 0xffff0000, v138
	v_lshlrev_b32_e32 v250, 16, v139
	v_and_b32_e32 v251, 0xffff0000, v139
	v_lshlrev_b32_e32 v252, 16, v140
	v_and_b32_e32 v253, 0xffff0000, v140
	v_lshlrev_b32_e32 v254, 16, v141
	v_and_b32_e32 v255, 0xffff0000, v141
	v_pk_mul_f32 v[118:119], v[118:119], v[248:249]
	v_pk_mul_f32 v[120:121], v[120:121], v[250:251]
	v_pk_mul_f32 v[110:111], v[110:111], v[252:253]
	v_pk_mul_f32 v[112:113], v[112:113], v[254:255]
	v_cvt_pk_bf16_f32 v138, v118, v119
	v_cvt_pk_bf16_f32 v139, v120, v121
	v_cvt_pk_bf16_f32 v140, v110, v111
	v_cvt_pk_bf16_f32 v141, v112, v113
	global_store_dwordx4 v233, v[138:141], s[6:7] offset:256
	s_waitcnt vmcnt(15)
	v_lshlrev_b32_e32 v248, 16, v142
	v_and_b32_e32 v249, 0xffff0000, v142
	v_lshlrev_b32_e32 v250, 16, v143
	v_and_b32_e32 v251, 0xffff0000, v143
	v_lshlrev_b32_e32 v252, 16, v144
	v_and_b32_e32 v253, 0xffff0000, v144
	v_lshlrev_b32_e32 v254, 16, v145
	v_and_b32_e32 v255, 0xffff0000, v145
	v_pk_mul_f32 v[122:123], v[122:123], v[248:249]
	v_pk_mul_f32 v[124:125], v[124:125], v[250:251]
	v_pk_mul_f32 v[114:115], v[114:115], v[252:253]
	v_pk_mul_f32 v[116:117], v[116:117], v[254:255]
	v_cvt_pk_bf16_f32 v142, v122, v123
	v_cvt_pk_bf16_f32 v143, v124, v125
	v_cvt_pk_bf16_f32 v144, v114, v115
	v_cvt_pk_bf16_f32 v145, v116, v117
	v_add_u32_e32 v233, 0x8000, v232
	global_store_dwordx4 v233, v[142:145], s[6:7]
	s_waitcnt vmcnt(15)
	v_lshlrev_b32_e32 v248, 16, v146
	v_and_b32_e32 v249, 0xffff0000, v146
	v_lshlrev_b32_e32 v250, 16, v147
	v_and_b32_e32 v251, 0xffff0000, v147
	v_lshlrev_b32_e32 v252, 16, v148
	v_and_b32_e32 v253, 0xffff0000, v148
	v_lshlrev_b32_e32 v254, 16, v149
	v_and_b32_e32 v255, 0xffff0000, v149
	v_pk_mul_f32 v[106:107], v[106:107], v[248:249]
	v_pk_mul_f32 v[108:109], v[108:109], v[250:251]
	v_pk_mul_f32 v[102:103], v[102:103], v[252:253]
	v_pk_mul_f32 v[104:105], v[104:105], v[254:255]
	v_cvt_pk_bf16_f32 v146, v106, v107
	v_cvt_pk_bf16_f32 v147, v108, v109
	v_cvt_pk_bf16_f32 v148, v102, v103
	v_cvt_pk_bf16_f32 v149, v104, v105
	global_store_dwordx4 v233, v[146:149], s[6:7] offset:256
	s_waitcnt vmcnt(15)
	v_lshlrev_b32_e32 v248, 16, v150
	v_and_b32_e32 v249, 0xffff0000, v150
	v_lshlrev_b32_e32 v250, 16, v151
	v_and_b32_e32 v251, 0xffff0000, v151
	v_lshlrev_b32_e32 v252, 16, v152
	v_and_b32_e32 v253, 0xffff0000, v152
	v_lshlrev_b32_e32 v254, 16, v153
	v_and_b32_e32 v255, 0xffff0000, v153
	v_pk_mul_f32 v[98:99], v[98:99], v[248:249]
	v_pk_mul_f32 v[100:101], v[100:101], v[250:251]
	v_pk_mul_f32 v[94:95], v[94:95], v[252:253]
	v_pk_mul_f32 v[96:97], v[96:97], v[254:255]
	v_cvt_pk_bf16_f32 v150, v98, v99
	v_cvt_pk_bf16_f32 v151, v100, v101
	v_cvt_pk_bf16_f32 v152, v94, v95
	v_cvt_pk_bf16_f32 v153, v96, v97
	v_add_u32_e32 v233, 0x10000, v232
	global_store_dwordx4 v233, v[150:153], s[6:7]
	s_waitcnt vmcnt(15)
	v_lshlrev_b32_e32 v248, 16, v154
	v_and_b32_e32 v249, 0xffff0000, v154
	v_lshlrev_b32_e32 v250, 16, v155
	v_and_b32_e32 v251, 0xffff0000, v155
	v_lshlrev_b32_e32 v252, 16, v156
	v_and_b32_e32 v253, 0xffff0000, v156
	v_lshlrev_b32_e32 v254, 16, v157
	v_and_b32_e32 v255, 0xffff0000, v157
	v_pk_mul_f32 v[90:91], v[90:91], v[248:249]
	v_pk_mul_f32 v[92:93], v[92:93], v[250:251]
	v_pk_mul_f32 v[86:87], v[86:87], v[252:253]
	v_pk_mul_f32 v[88:89], v[88:89], v[254:255]
	v_cvt_pk_bf16_f32 v154, v90, v91
	v_cvt_pk_bf16_f32 v155, v92, v93
	v_cvt_pk_bf16_f32 v156, v86, v87
	v_cvt_pk_bf16_f32 v157, v88, v89
	global_store_dwordx4 v233, v[154:157], s[6:7] offset:256
	s_waitcnt vmcnt(15)
	v_lshlrev_b32_e32 v248, 16, v158
	v_and_b32_e32 v249, 0xffff0000, v158
	v_lshlrev_b32_e32 v250, 16, v159
	v_and_b32_e32 v251, 0xffff0000, v159
	v_lshlrev_b32_e32 v252, 16, v160
	v_and_b32_e32 v253, 0xffff0000, v160
	v_lshlrev_b32_e32 v254, 16, v161
	v_and_b32_e32 v255, 0xffff0000, v161
	v_pk_mul_f32 v[82:83], v[82:83], v[248:249]
	v_pk_mul_f32 v[84:85], v[84:85], v[250:251]
	v_pk_mul_f32 v[78:79], v[78:79], v[252:253]
	v_pk_mul_f32 v[80:81], v[80:81], v[254:255]
	v_cvt_pk_bf16_f32 v158, v82, v83
	v_cvt_pk_bf16_f32 v159, v84, v85
	v_cvt_pk_bf16_f32 v160, v78, v79
	v_cvt_pk_bf16_f32 v161, v80, v81
	v_add_u32_e32 v233, 0x18000, v232
	global_store_dwordx4 v233, v[158:161], s[6:7]
	s_waitcnt vmcnt(15)
	v_lshlrev_b32_e32 v248, 16, v192
	v_and_b32_e32 v249, 0xffff0000, v192
	v_lshlrev_b32_e32 v250, 16, v193
	v_and_b32_e32 v251, 0xffff0000, v193
	v_lshlrev_b32_e32 v252, 16, v194
	v_and_b32_e32 v253, 0xffff0000, v194
	v_lshlrev_b32_e32 v254, 16, v195
	v_and_b32_e32 v255, 0xffff0000, v195
	v_pk_mul_f32 v[74:75], v[74:75], v[248:249]
	v_pk_mul_f32 v[76:77], v[76:77], v[250:251]
	v_pk_mul_f32 v[70:71], v[70:71], v[252:253]
	v_pk_mul_f32 v[72:73], v[72:73], v[254:255]
	v_cvt_pk_bf16_f32 v192, v74, v75
	v_cvt_pk_bf16_f32 v193, v76, v77
	v_cvt_pk_bf16_f32 v194, v70, v71
	v_cvt_pk_bf16_f32 v195, v72, v73
	global_store_dwordx4 v233, v[192:195], s[6:7] offset:256
	s_waitcnt vmcnt(15)
	v_lshlrev_b32_e32 v248, 16, v196
	v_and_b32_e32 v249, 0xffff0000, v196
	v_lshlrev_b32_e32 v250, 16, v197
	v_and_b32_e32 v251, 0xffff0000, v197
	v_lshlrev_b32_e32 v252, 16, v198
	v_and_b32_e32 v253, 0xffff0000, v198
	v_lshlrev_b32_e32 v254, 16, v199
	v_and_b32_e32 v255, 0xffff0000, v199
	v_pk_mul_f32 v[66:67], v[66:67], v[248:249]
	v_pk_mul_f32 v[68:69], v[68:69], v[250:251]
	v_pk_mul_f32 v[62:63], v[62:63], v[252:253]
	v_pk_mul_f32 v[64:65], v[64:65], v[254:255]
	v_cvt_pk_bf16_f32 v196, v66, v67
	v_cvt_pk_bf16_f32 v197, v68, v69
	v_cvt_pk_bf16_f32 v198, v62, v63
	v_cvt_pk_bf16_f32 v199, v64, v65
	v_add_u32_e32 v233, 0x40000, v232
	global_store_dwordx4 v233, v[196:199], s[6:7]
	s_waitcnt vmcnt(15)
	v_lshlrev_b32_e32 v248, 16, v200
	v_and_b32_e32 v249, 0xffff0000, v200
	v_lshlrev_b32_e32 v250, 16, v201
	v_and_b32_e32 v251, 0xffff0000, v201
	v_lshlrev_b32_e32 v252, 16, v202
	v_and_b32_e32 v253, 0xffff0000, v202
	v_lshlrev_b32_e32 v254, 16, v203
	v_and_b32_e32 v255, 0xffff0000, v203
	v_pk_mul_f32 v[58:59], v[58:59], v[248:249]
	v_pk_mul_f32 v[60:61], v[60:61], v[250:251]
	v_pk_mul_f32 v[54:55], v[54:55], v[252:253]
	v_pk_mul_f32 v[56:57], v[56:57], v[254:255]
	v_cvt_pk_bf16_f32 v200, v58, v59
	v_cvt_pk_bf16_f32 v201, v60, v61
	v_cvt_pk_bf16_f32 v202, v54, v55
	v_cvt_pk_bf16_f32 v203, v56, v57
	global_store_dwordx4 v233, v[200:203], s[6:7] offset:256
	s_waitcnt vmcnt(15)
	v_lshlrev_b32_e32 v248, 16, v204
	v_and_b32_e32 v249, 0xffff0000, v204
	v_lshlrev_b32_e32 v250, 16, v205
	v_and_b32_e32 v251, 0xffff0000, v205
	v_lshlrev_b32_e32 v252, 16, v206
	v_and_b32_e32 v253, 0xffff0000, v206
	v_lshlrev_b32_e32 v254, 16, v207
	v_and_b32_e32 v255, 0xffff0000, v207
	v_pk_mul_f32 v[50:51], v[50:51], v[248:249]
	v_pk_mul_f32 v[52:53], v[52:53], v[250:251]
	v_pk_mul_f32 v[46:47], v[46:47], v[252:253]
	v_pk_mul_f32 v[48:49], v[48:49], v[254:255]
	v_cvt_pk_bf16_f32 v204, v50, v51
	v_cvt_pk_bf16_f32 v205, v52, v53
	v_cvt_pk_bf16_f32 v206, v46, v47
	v_cvt_pk_bf16_f32 v207, v48, v49
	v_add_u32_e32 v233, 0x48000, v232
	global_store_dwordx4 v233, v[204:207], s[6:7]
	s_waitcnt vmcnt(15)
	v_lshlrev_b32_e32 v248, 16, v208
	v_and_b32_e32 v249, 0xffff0000, v208
	v_lshlrev_b32_e32 v250, 16, v209
	v_and_b32_e32 v251, 0xffff0000, v209
	v_lshlrev_b32_e32 v252, 16, v210
	v_and_b32_e32 v253, 0xffff0000, v210
	v_lshlrev_b32_e32 v254, 16, v211
	v_and_b32_e32 v255, 0xffff0000, v211
	v_pk_mul_f32 v[42:43], v[42:43], v[248:249]
	v_pk_mul_f32 v[44:45], v[44:45], v[250:251]
	v_pk_mul_f32 v[38:39], v[38:39], v[252:253]
	v_pk_mul_f32 v[40:41], v[40:41], v[254:255]
	v_cvt_pk_bf16_f32 v208, v42, v43
	v_cvt_pk_bf16_f32 v209, v44, v45
	v_cvt_pk_bf16_f32 v210, v38, v39
	v_cvt_pk_bf16_f32 v211, v40, v41
	global_store_dwordx4 v233, v[208:211], s[6:7] offset:256
	s_waitcnt vmcnt(15)
	v_lshlrev_b32_e32 v248, 16, v212
	v_and_b32_e32 v249, 0xffff0000, v212
	v_lshlrev_b32_e32 v250, 16, v213
	v_and_b32_e32 v251, 0xffff0000, v213
	v_lshlrev_b32_e32 v252, 16, v214
	v_and_b32_e32 v253, 0xffff0000, v214
	v_lshlrev_b32_e32 v254, 16, v215
	v_and_b32_e32 v255, 0xffff0000, v215
	v_pk_mul_f32 v[34:35], v[34:35], v[248:249]
	v_pk_mul_f32 v[36:37], v[36:37], v[250:251]
	v_pk_mul_f32 v[30:31], v[30:31], v[252:253]
	v_pk_mul_f32 v[32:33], v[32:33], v[254:255]
	v_cvt_pk_bf16_f32 v212, v34, v35
	v_cvt_pk_bf16_f32 v213, v36, v37
	v_cvt_pk_bf16_f32 v214, v30, v31
	v_cvt_pk_bf16_f32 v215, v32, v33
	v_add_u32_e32 v233, 0x50000, v232
	global_store_dwordx4 v233, v[212:215], s[6:7]
	s_waitcnt vmcnt(15)
	v_lshlrev_b32_e32 v248, 16, v216
	v_and_b32_e32 v249, 0xffff0000, v216
	v_lshlrev_b32_e32 v250, 16, v217
	v_and_b32_e32 v251, 0xffff0000, v217
	v_lshlrev_b32_e32 v252, 16, v218
	v_and_b32_e32 v253, 0xffff0000, v218
	v_lshlrev_b32_e32 v254, 16, v219
	v_and_b32_e32 v255, 0xffff0000, v219
	v_pk_mul_f32 v[26:27], v[26:27], v[248:249]
	v_pk_mul_f32 v[28:29], v[28:29], v[250:251]
	v_pk_mul_f32 v[22:23], v[22:23], v[252:253]
	v_pk_mul_f32 v[24:25], v[24:25], v[254:255]
	v_cvt_pk_bf16_f32 v216, v26, v27
	v_cvt_pk_bf16_f32 v217, v28, v29
	v_cvt_pk_bf16_f32 v218, v22, v23
	v_cvt_pk_bf16_f32 v219, v24, v25
	global_store_dwordx4 v233, v[216:219], s[6:7] offset:256
	s_waitcnt vmcnt(15)
	v_lshlrev_b32_e32 v248, 16, v220
	v_and_b32_e32 v249, 0xffff0000, v220
	v_lshlrev_b32_e32 v250, 16, v221
	v_and_b32_e32 v251, 0xffff0000, v221
	v_lshlrev_b32_e32 v252, 16, v222
	v_and_b32_e32 v253, 0xffff0000, v222
	v_lshlrev_b32_e32 v254, 16, v223
	v_and_b32_e32 v255, 0xffff0000, v223
	v_pk_mul_f32 v[18:19], v[18:19], v[248:249]
	v_pk_mul_f32 v[20:21], v[20:21], v[250:251]
	v_pk_mul_f32 v[14:15], v[14:15], v[252:253]
	v_pk_mul_f32 v[16:17], v[16:17], v[254:255]
	v_cvt_pk_bf16_f32 v220, v18, v19
	v_cvt_pk_bf16_f32 v221, v20, v21
	v_cvt_pk_bf16_f32 v222, v14, v15
	v_cvt_pk_bf16_f32 v223, v16, v17
	v_add_u32_e32 v233, 0x58000, v232
	global_store_dwordx4 v233, v[220:223], s[6:7]
	s_waitcnt vmcnt(15)
	v_lshlrev_b32_e32 v248, 16, v224
	v_and_b32_e32 v249, 0xffff0000, v224
	v_lshlrev_b32_e32 v250, 16, v225
	v_and_b32_e32 v251, 0xffff0000, v225
	v_lshlrev_b32_e32 v252, 16, v226
	v_and_b32_e32 v253, 0xffff0000, v226
	v_lshlrev_b32_e32 v254, 16, v227
	v_and_b32_e32 v255, 0xffff0000, v227
	v_pk_mul_f32 v[10:11], v[10:11], v[248:249]
	v_pk_mul_f32 v[12:13], v[12:13], v[250:251]
	v_pk_mul_f32 v[6:7], v[6:7], v[252:253]
	v_pk_mul_f32 v[8:9], v[8:9], v[254:255]
	v_cvt_pk_bf16_f32 v224, v10, v11
	v_cvt_pk_bf16_f32 v225, v12, v13
	v_cvt_pk_bf16_f32 v226, v6, v7
	v_cvt_pk_bf16_f32 v227, v8, v9
	global_store_dwordx4 v233, v[224:227], s[6:7] offset:256
	s_cbranch_vccnz .LBB0_626

.LBB0_624:
	s_cmpk_lg_i32 s40, 0x800
	s_cbranch_scc1 .LBB0_623
	v_lshlrev_b32_e32 v3, 10, v180
	v_add_lshl_u32 v3, v3, v182, 1
	v_mov_b32_e32 v4, v3
	global_load_dwordx4 v[192:195], v4, s[8:9]
	global_load_dwordx4 v[196:199], v4, s[10:11]
	global_load_dwordx4 v[200:203], v4, s[8:9] offset:256
	global_load_dwordx4 v[204:207], v4, s[10:11] offset:256
	v_add_u32_e32 v4, 0x8000, v3
	global_load_dwordx4 v[208:211], v4, s[8:9]
	global_load_dwordx4 v[212:215], v4, s[10:11]
	global_load_dwordx4 v[216:219], v4, s[8:9] offset:256
	global_load_dwordx4 v[220:223], v4, s[10:11] offset:256
	v_add_u32_e32 v4, 0x10000, v3
	global_load_dwordx4 v[224:227], v4, s[8:9]
	global_load_dwordx4 v[228:231], v4, s[10:11]
	global_load_dwordx4 v[134:137], v4, s[8:9] offset:256
	global_load_dwordx4 v[138:141], v4, s[10:11] offset:256
	v_add_u32_e32 v4, 0x18000, v3
	global_load_dwordx4 v[142:145], v4, s[8:9]
	global_load_dwordx4 v[146:149], v4, s[10:11]
	global_load_dwordx4 v[150:153], v4, s[8:9] offset:256
	global_load_dwordx4 v[154:157], v4, s[10:11] offset:256
	s_waitcnt vmcnt(14)
	v_lshlrev_b32_e32 v248, 16, v196
	v_and_b32_e32 v249, 0xffff0000, v196
	v_lshlrev_b32_e32 v250, 16, v197
	v_and_b32_e32 v251, 0xffff0000, v197
	v_lshlrev_b32_e32 v252, 16, v198
	v_and_b32_e32 v253, 0xffff0000, v198
	v_lshlrev_b32_e32 v254, 16, v199
	v_and_b32_e32 v255, 0xffff0000, v199
	v_lshlrev_b32_e32 v158, 16, v192
	v_and_b32_e32 v159, 0xffff0000, v192
	v_lshlrev_b32_e32 v160, 16, v193
	v_and_b32_e32 v161, 0xffff0000, v193
	v_lshlrev_b32_e32 v162, 16, v194
	v_and_b32_e32 v163, 0xffff0000, v194
	v_lshlrev_b32_e32 v232, 16, v195
	v_and_b32_e32 v233, 0xffff0000, v195
	v_add_u32_e32 v4, 0x40000, v3
	global_load_dwordx4 v[192:195], v4, s[8:9]
	global_load_dwordx4 v[196:199], v4, s[10:11]
	v_max_f32_e32 v248, 0xda24260, v248
	v_max_f32_e32 v249, 0xda24260, v249
	v_max_f32_e32 v250, 0xda24260, v250
	v_max_f32_e32 v251, 0xda24260, v251
	v_max_f32_e32 v252, 0xda24260, v252
	v_max_f32_e32 v253, 0xda24260, v253
	v_max_f32_e32 v254, 0xda24260, v254
	v_max_f32_e32 v255, 0xda24260, v255
	v_rcp_f32_e32 v248, v248
	v_rcp_f32_e32 v249, v249
	v_rcp_f32_e32 v250, v250
	v_rcp_f32_e32 v251, v251
	v_rcp_f32_e32 v252, v252
	v_rcp_f32_e32 v253, v253
	v_rcp_f32_e32 v254, v254
	v_rcp_f32_e32 v255, v255
	s_nop 0
	v_pk_mul_f32 v[158:159], v[248:249], v[158:159]
	v_pk_mul_f32 v[160:161], v[250:251], v[160:161]
	v_pk_mul_f32 v[162:163], v[252:253], v[162:163]
	v_pk_mul_f32 v[232:233], v[254:255], v[232:233]
	v_pk_mul_f32 v[130:131], v[130:131], v[158:159]
	v_pk_mul_f32 v[132:133], v[132:133], v[160:161]
	v_pk_mul_f32 v[126:127], v[126:127], v[162:163]
	v_pk_mul_f32 v[128:129], v[128:129], v[232:233]
	s_waitcnt vmcnt(14)
	v_lshlrev_b32_e32 v248, 16, v204
	v_and_b32_e32 v249, 0xffff0000, v204
	v_lshlrev_b32_e32 v250, 16, v205
	v_and_b32_e32 v251, 0xffff0000, v205
	v_lshlrev_b32_e32 v252, 16, v206
	v_and_b32_e32 v253, 0xffff0000, v206
	v_lshlrev_b32_e32 v254, 16, v207
	v_and_b32_e32 v255, 0xffff0000, v207
	v_lshlrev_b32_e32 v158, 16, v200
	v_and_b32_e32 v159, 0xffff0000, v200
	v_lshlrev_b32_e32 v160, 16, v201
	v_and_b32_e32 v161, 0xffff0000, v201
	v_lshlrev_b32_e32 v162, 16, v202
	v_and_b32_e32 v163, 0xffff0000, v202
	v_lshlrev_b32_e32 v232, 16, v203
	v_and_b32_e32 v233, 0xffff0000, v203
	global_load_dwordx4 v[200:203], v4, s[8:9] offset:256
	global_load_dwordx4 v[204:207], v4, s[10:11] offset:256
	v_max_f32_e32 v248, 0xda24260, v248
	v_max_f32_e32 v249, 0xda24260, v249
	v_max_f32_e32 v250, 0xda24260, v250
	v_max_f32_e32 v251, 0xda24260, v251
	v_max_f32_e32 v252, 0xda24260, v252
	v_max_f32_e32 v253, 0xda24260, v253
	v_max_f32_e32 v254, 0xda24260, v254
	v_max_f32_e32 v255, 0xda24260, v255
	v_rcp_f32_e32 v248, v248
	v_rcp_f32_e32 v249, v249
	v_rcp_f32_e32 v250, v250
	v_rcp_f32_e32 v251, v251
	v_rcp_f32_e32 v252, v252
	v_rcp_f32_e32 v253, v253
	v_rcp_f32_e32 v254, v254
	v_rcp_f32_e32 v255, v255
	s_nop 0
	v_pk_mul_f32 v[158:159], v[248:249], v[158:159]
	v_pk_mul_f32 v[160:161], v[250:251], v[160:161]
	v_pk_mul_f32 v[162:163], v[252:253], v[162:163]
	v_pk_mul_f32 v[232:233], v[254:255], v[232:233]
	v_pk_mul_f32 v[118:119], v[118:119], v[158:159]
	v_pk_mul_f32 v[120:121], v[120:121], v[160:161]
	v_pk_mul_f32 v[110:111], v[110:111], v[162:163]
	v_pk_mul_f32 v[112:113], v[112:113], v[232:233]
	s_waitcnt vmcnt(14)
	v_lshlrev_b32_e32 v248, 16, v212
	v_and_b32_e32 v249, 0xffff0000, v212
	v_lshlrev_b32_e32 v250, 16, v213
	v_and_b32_e32 v251, 0xffff0000, v213
	v_lshlrev_b32_e32 v252, 16, v214
	v_and_b32_e32 v253, 0xffff0000, v214
	v_lshlrev_b32_e32 v254, 16, v215
	v_and_b32_e32 v255, 0xffff0000, v215
	v_lshlrev_b32_e32 v158, 16, v208
	v_and_b32_e32 v159, 0xffff0000, v208
	v_lshlrev_b32_e32 v160, 16, v209
	v_and_b32_e32 v161, 0xffff0000, v209
	v_lshlrev_b32_e32 v162, 16, v210
	v_and_b32_e32 v163, 0xffff0000, v210
	v_lshlrev_b32_e32 v232, 16, v211
	v_and_b32_e32 v233, 0xffff0000, v211
	v_add_u32_e32 v4, 0x48000, v3
	global_load_dwordx4 v[208:211], v4, s[8:9]
	global_load_dwordx4 v[212:215], v4, s[10:11]
	v_max_f32_e32 v248, 0xda24260, v248
	v_max_f32_e32 v249, 0xda24260, v249
	v_max_f32_e32 v250, 0xda24260, v250
	v_max_f32_e32 v251, 0xda24260, v251
	v_max_f32_e32 v252, 0xda24260, v252
	v_max_f32_e32 v253, 0xda24260, v253
	v_max_f32_e32 v254, 0xda24260, v254
	v_max_f32_e32 v255, 0xda24260, v255
	v_rcp_f32_e32 v248, v248
	v_rcp_f32_e32 v249, v249
	v_rcp_f32_e32 v250, v250
	v_rcp_f32_e32 v251, v251
	v_rcp_f32_e32 v252, v252
	v_rcp_f32_e32 v253, v253
	v_rcp_f32_e32 v254, v254
	v_rcp_f32_e32 v255, v255
	s_nop 0
	v_pk_mul_f32 v[158:159], v[248:249], v[158:159]
	v_pk_mul_f32 v[160:161], v[250:251], v[160:161]
	v_pk_mul_f32 v[162:163], v[252:253], v[162:163]
	v_pk_mul_f32 v[232:233], v[254:255], v[232:233]
	v_pk_mul_f32 v[122:123], v[122:123], v[158:159]
	v_pk_mul_f32 v[124:125], v[124:125], v[160:161]
	v_pk_mul_f32 v[114:115], v[114:115], v[162:163]
	v_pk_mul_f32 v[116:117], v[116:117], v[232:233]
	s_waitcnt vmcnt(14)
	v_lshlrev_b32_e32 v248, 16, v220
	v_and_b32_e32 v249, 0xffff0000, v220
	v_lshlrev_b32_e32 v250, 16, v221
	v_and_b32_e32 v251, 0xffff0000, v221
	v_lshlrev_b32_e32 v252, 16, v222
	v_and_b32_e32 v253, 0xffff0000, v222
	v_lshlrev_b32_e32 v254, 16, v223
	v_and_b32_e32 v255, 0xffff0000, v223
	v_lshlrev_b32_e32 v158, 16, v216
	v_and_b32_e32 v159, 0xffff0000, v216
	v_lshlrev_b32_e32 v160, 16, v217
	v_and_b32_e32 v161, 0xffff0000, v217
	v_lshlrev_b32_e32 v162, 16, v218
	v_and_b32_e32 v163, 0xffff0000, v218
	v_lshlrev_b32_e32 v232, 16, v219
	v_and_b32_e32 v233, 0xffff0000, v219
	global_load_dwordx4 v[216:219], v4, s[8:9] offset:256
	global_load_dwordx4 v[220:223], v4, s[10:11] offset:256
	v_max_f32_e32 v248, 0xda24260, v248
	v_max_f32_e32 v249, 0xda24260, v249
	v_max_f32_e32 v250, 0xda24260, v250
	v_max_f32_e32 v251, 0xda24260, v251
	v_max_f32_e32 v252, 0xda24260, v252
	v_max_f32_e32 v253, 0xda24260, v253
	v_max_f32_e32 v254, 0xda24260, v254
	v_max_f32_e32 v255, 0xda24260, v255
	v_rcp_f32_e32 v248, v248
	v_rcp_f32_e32 v249, v249
	v_rcp_f32_e32 v250, v250
	v_rcp_f32_e32 v251, v251
	v_rcp_f32_e32 v252, v252
	v_rcp_f32_e32 v253, v253
	v_rcp_f32_e32 v254, v254
	v_rcp_f32_e32 v255, v255
	s_nop 0
	v_pk_mul_f32 v[158:159], v[248:249], v[158:159]
	v_pk_mul_f32 v[160:161], v[250:251], v[160:161]
	v_pk_mul_f32 v[162:163], v[252:253], v[162:163]
	v_pk_mul_f32 v[232:233], v[254:255], v[232:233]
	v_pk_mul_f32 v[106:107], v[106:107], v[158:159]
	v_pk_mul_f32 v[108:109], v[108:109], v[160:161]
	v_pk_mul_f32 v[102:103], v[102:103], v[162:163]
	v_pk_mul_f32 v[104:105], v[104:105], v[232:233]
	s_waitcnt vmcnt(14)
	v_lshlrev_b32_e32 v248, 16, v228
	v_and_b32_e32 v249, 0xffff0000, v228
	v_lshlrev_b32_e32 v250, 16, v229
	v_and_b32_e32 v251, 0xffff0000, v229
	v_lshlrev_b32_e32 v252, 16, v230
	v_and_b32_e32 v253, 0xffff0000, v230
	v_lshlrev_b32_e32 v254, 16, v231
	v_and_b32_e32 v255, 0xffff0000, v231
	v_lshlrev_b32_e32 v158, 16, v224
	v_and_b32_e32 v159, 0xffff0000, v224
	v_lshlrev_b32_e32 v160, 16, v225
	v_and_b32_e32 v161, 0xffff0000, v225
	v_lshlrev_b32_e32 v162, 16, v226
	v_and_b32_e32 v163, 0xffff0000, v226
	v_lshlrev_b32_e32 v232, 16, v227
	v_and_b32_e32 v233, 0xffff0000, v227
	v_add_u32_e32 v4, 0x50000, v3
	global_load_dwordx4 v[224:227], v4, s[8:9]
	global_load_dwordx4 v[228:231], v4, s[10:11]
	v_max_f32_e32 v248, 0xda24260, v248
	v_max_f32_e32 v249, 0xda24260, v249
	v_max_f32_e32 v250, 0xda24260, v250
	v_max_f32_e32 v251, 0xda24260, v251
	v_max_f32_e32 v252, 0xda24260, v252
	v_max_f32_e32 v253, 0xda24260, v253
	v_max_f32_e32 v254, 0xda24260, v254
	v_max_f32_e32 v255, 0xda24260, v255
	v_rcp_f32_e32 v248, v248
	v_rcp_f32_e32 v249, v249
	v_rcp_f32_e32 v250, v250
	v_rcp_f32_e32 v251, v251
	v_rcp_f32_e32 v252, v252
	v_rcp_f32_e32 v253, v253
	v_rcp_f32_e32 v254, v254
	v_rcp_f32_e32 v255, v255
	s_nop 0
	v_pk_mul_f32 v[158:159], v[248:249], v[158:159]
	v_pk_mul_f32 v[160:161], v[250:251], v[160:161]
	v_pk_mul_f32 v[162:163], v[252:253], v[162:163]
	v_pk_mul_f32 v[232:233], v[254:255], v[232:233]
	v_pk_mul_f32 v[98:99], v[98:99], v[158:159]
	v_pk_mul_f32 v[100:101], v[100:101], v[160:161]
	v_pk_mul_f32 v[94:95], v[94:95], v[162:163]
	v_pk_mul_f32 v[96:97], v[96:97], v[232:233]
	s_waitcnt vmcnt(14)
	v_lshlrev_b32_e32 v248, 16, v138
	v_and_b32_e32 v249, 0xffff0000, v138
	v_lshlrev_b32_e32 v250, 16, v139
	v_and_b32_e32 v251, 0xffff0000, v139
	v_lshlrev_b32_e32 v252, 16, v140
	v_and_b32_e32 v253, 0xffff0000, v140
	v_lshlrev_b32_e32 v254, 16, v141
	v_and_b32_e32 v255, 0xffff0000, v141
	v_lshlrev_b32_e32 v158, 16, v134
	v_and_b32_e32 v159, 0xffff0000, v134
	v_lshlrev_b32_e32 v160, 16, v135
	v_and_b32_e32 v161, 0xffff0000, v135
	v_lshlrev_b32_e32 v162, 16, v136
	v_and_b32_e32 v163, 0xffff0000, v136
	v_lshlrev_b32_e32 v232, 16, v137
	v_and_b32_e32 v233, 0xffff0000, v137
	global_load_dwordx4 v[134:137], v4, s[8:9] offset:256
	global_load_dwordx4 v[138:141], v4, s[10:11] offset:256
	v_max_f32_e32 v248, 0xda24260, v248
	v_max_f32_e32 v249, 0xda24260, v249
	v_max_f32_e32 v250, 0xda24260, v250
	v_max_f32_e32 v251, 0xda24260, v251
	v_max_f32_e32 v252, 0xda24260, v252
	v_max_f32_e32 v253, 0xda24260, v253
	v_max_f32_e32 v254, 0xda24260, v254
	v_max_f32_e32 v255, 0xda24260, v255
	v_rcp_f32_e32 v248, v248
	v_rcp_f32_e32 v249, v249
	v_rcp_f32_e32 v250, v250
	v_rcp_f32_e32 v251, v251
	v_rcp_f32_e32 v252, v252
	v_rcp_f32_e32 v253, v253
	v_rcp_f32_e32 v254, v254
	v_rcp_f32_e32 v255, v255
	s_nop 0
	v_pk_mul_f32 v[158:159], v[248:249], v[158:159]
	v_pk_mul_f32 v[160:161], v[250:251], v[160:161]
	v_pk_mul_f32 v[162:163], v[252:253], v[162:163]
	v_pk_mul_f32 v[232:233], v[254:255], v[232:233]
	v_pk_mul_f32 v[90:91], v[90:91], v[158:159]
	v_pk_mul_f32 v[92:93], v[92:93], v[160:161]
	v_pk_mul_f32 v[86:87], v[86:87], v[162:163]
	v_pk_mul_f32 v[88:89], v[88:89], v[232:233]
	s_waitcnt vmcnt(14)
	v_lshlrev_b32_e32 v248, 16, v146
	v_and_b32_e32 v249, 0xffff0000, v146
	v_lshlrev_b32_e32 v250, 16, v147
	v_and_b32_e32 v251, 0xffff0000, v147
	v_lshlrev_b32_e32 v252, 16, v148
	v_and_b32_e32 v253, 0xffff0000, v148
	v_lshlrev_b32_e32 v254, 16, v149
	v_and_b32_e32 v255, 0xffff0000, v149
	v_lshlrev_b32_e32 v158, 16, v142
	v_and_b32_e32 v159, 0xffff0000, v142
	v_lshlrev_b32_e32 v160, 16, v143
	v_and_b32_e32 v161, 0xffff0000, v143
	v_lshlrev_b32_e32 v162, 16, v144
	v_and_b32_e32 v163, 0xffff0000, v144
	v_lshlrev_b32_e32 v232, 16, v145
	v_and_b32_e32 v233, 0xffff0000, v145
	v_add_u32_e32 v4, 0x58000, v3
	global_load_dwordx4 v[142:145], v4, s[8:9]
	global_load_dwordx4 v[146:149], v4, s[10:11]
	v_max_f32_e32 v248, 0xda24260, v248
	v_max_f32_e32 v249, 0xda24260, v249
	v_max_f32_e32 v250, 0xda24260, v250
	v_max_f32_e32 v251, 0xda24260, v251
	v_max_f32_e32 v252, 0xda24260, v252
	v_max_f32_e32 v253, 0xda24260, v253
	v_max_f32_e32 v254, 0xda24260, v254
	v_max_f32_e32 v255, 0xda24260, v255
	v_rcp_f32_e32 v248, v248
	v_rcp_f32_e32 v249, v249
	v_rcp_f32_e32 v250, v250
	v_rcp_f32_e32 v251, v251
	v_rcp_f32_e32 v252, v252
	v_rcp_f32_e32 v253, v253
	v_rcp_f32_e32 v254, v254
	v_rcp_f32_e32 v255, v255
	s_nop 0
	v_pk_mul_f32 v[158:159], v[248:249], v[158:159]
	v_pk_mul_f32 v[160:161], v[250:251], v[160:161]
	v_pk_mul_f32 v[162:163], v[252:253], v[162:163]
	v_pk_mul_f32 v[232:233], v[254:255], v[232:233]
	v_pk_mul_f32 v[82:83], v[82:83], v[158:159]
	v_pk_mul_f32 v[84:85], v[84:85], v[160:161]
	v_pk_mul_f32 v[78:79], v[78:79], v[162:163]
	v_pk_mul_f32 v[80:81], v[80:81], v[232:233]
	s_waitcnt vmcnt(14)
	v_lshlrev_b32_e32 v248, 16, v154
	v_and_b32_e32 v249, 0xffff0000, v154
	v_lshlrev_b32_e32 v250, 16, v155
	v_and_b32_e32 v251, 0xffff0000, v155
	v_lshlrev_b32_e32 v252, 16, v156
	v_and_b32_e32 v253, 0xffff0000, v156
	v_lshlrev_b32_e32 v254, 16, v157
	v_and_b32_e32 v255, 0xffff0000, v157
	v_lshlrev_b32_e32 v158, 16, v150
	v_and_b32_e32 v159, 0xffff0000, v150
	v_lshlrev_b32_e32 v160, 16, v151
	v_and_b32_e32 v161, 0xffff0000, v151
	v_lshlrev_b32_e32 v162, 16, v152
	v_and_b32_e32 v163, 0xffff0000, v152
	v_lshlrev_b32_e32 v232, 16, v153
	v_and_b32_e32 v233, 0xffff0000, v153
	global_load_dwordx4 v[150:153], v4, s[8:9] offset:256
	global_load_dwordx4 v[154:157], v4, s[10:11] offset:256
	v_max_f32_e32 v248, 0xda24260, v248
	v_max_f32_e32 v249, 0xda24260, v249
	v_max_f32_e32 v250, 0xda24260, v250
	v_max_f32_e32 v251, 0xda24260, v251
	v_max_f32_e32 v252, 0xda24260, v252
	v_max_f32_e32 v253, 0xda24260, v253
	v_max_f32_e32 v254, 0xda24260, v254
	v_max_f32_e32 v255, 0xda24260, v255
	v_rcp_f32_e32 v248, v248
	v_rcp_f32_e32 v249, v249
	v_rcp_f32_e32 v250, v250
	v_rcp_f32_e32 v251, v251
	v_rcp_f32_e32 v252, v252
	v_rcp_f32_e32 v253, v253
	v_rcp_f32_e32 v254, v254
	v_rcp_f32_e32 v255, v255
	s_nop 0
	v_pk_mul_f32 v[158:159], v[248:249], v[158:159]
	v_pk_mul_f32 v[160:161], v[250:251], v[160:161]
	v_pk_mul_f32 v[162:163], v[252:253], v[162:163]
	v_pk_mul_f32 v[232:233], v[254:255], v[232:233]
	v_pk_mul_f32 v[74:75], v[74:75], v[158:159]
	v_pk_mul_f32 v[76:77], v[76:77], v[160:161]
	v_pk_mul_f32 v[70:71], v[70:71], v[162:163]
	v_pk_mul_f32 v[72:73], v[72:73], v[232:233]
	s_waitcnt vmcnt(14)
	v_lshlrev_b32_e32 v248, 16, v196
	v_and_b32_e32 v249, 0xffff0000, v196
	v_lshlrev_b32_e32 v250, 16, v197
	v_and_b32_e32 v251, 0xffff0000, v197
	v_lshlrev_b32_e32 v252, 16, v198
	v_and_b32_e32 v253, 0xffff0000, v198
	v_lshlrev_b32_e32 v254, 16, v199
	v_and_b32_e32 v255, 0xffff0000, v199
	v_lshlrev_b32_e32 v158, 16, v192
	v_and_b32_e32 v159, 0xffff0000, v192
	v_lshlrev_b32_e32 v160, 16, v193
	v_and_b32_e32 v161, 0xffff0000, v193
	v_lshlrev_b32_e32 v162, 16, v194
	v_and_b32_e32 v163, 0xffff0000, v194
	v_lshlrev_b32_e32 v232, 16, v195
	v_and_b32_e32 v233, 0xffff0000, v195
	v_max_f32_e32 v248, 0xda24260, v248
	v_max_f32_e32 v249, 0xda24260, v249
	v_max_f32_e32 v250, 0xda24260, v250
	v_max_f32_e32 v251, 0xda24260, v251
	v_max_f32_e32 v252, 0xda24260, v252
	v_max_f32_e32 v253, 0xda24260, v253
	v_max_f32_e32 v254, 0xda24260, v254
	v_max_f32_e32 v255, 0xda24260, v255
	v_rcp_f32_e32 v248, v248
	v_rcp_f32_e32 v249, v249
	v_rcp_f32_e32 v250, v250
	v_rcp_f32_e32 v251, v251
	v_rcp_f32_e32 v252, v252
	v_rcp_f32_e32 v253, v253
	v_rcp_f32_e32 v254, v254
	v_rcp_f32_e32 v255, v255
	s_nop 0
	v_pk_mul_f32 v[158:159], v[248:249], v[158:159]
	v_pk_mul_f32 v[160:161], v[250:251], v[160:161]
	v_pk_mul_f32 v[162:163], v[252:253], v[162:163]
	v_pk_mul_f32 v[232:233], v[254:255], v[232:233]
	v_pk_mul_f32 v[66:67], v[66:67], v[158:159]
	v_pk_mul_f32 v[68:69], v[68:69], v[160:161]
	v_pk_mul_f32 v[62:63], v[62:63], v[162:163]
	v_pk_mul_f32 v[64:65], v[64:65], v[232:233]
	s_waitcnt vmcnt(12)
	v_lshlrev_b32_e32 v248, 16, v204
	v_and_b32_e32 v249, 0xffff0000, v204
	v_lshlrev_b32_e32 v250, 16, v205
	v_and_b32_e32 v251, 0xffff0000, v205
	v_lshlrev_b32_e32 v252, 16, v206
	v_and_b32_e32 v253, 0xffff0000, v206
	v_lshlrev_b32_e32 v254, 16, v207
	v_and_b32_e32 v255, 0xffff0000, v207
	v_lshlrev_b32_e32 v158, 16, v200
	v_and_b32_e32 v159, 0xffff0000, v200
	v_lshlrev_b32_e32 v160, 16, v201
	v_and_b32_e32 v161, 0xffff0000, v201
	v_lshlrev_b32_e32 v162, 16, v202
	v_and_b32_e32 v163, 0xffff0000, v202
	v_lshlrev_b32_e32 v232, 16, v203
	v_and_b32_e32 v233, 0xffff0000, v203
	v_max_f32_e32 v248, 0xda24260, v248
	v_max_f32_e32 v249, 0xda24260, v249
	v_max_f32_e32 v250, 0xda24260, v250
	v_max_f32_e32 v251, 0xda24260, v251
	v_max_f32_e32 v252, 0xda24260, v252
	v_max_f32_e32 v253, 0xda24260, v253
	v_max_f32_e32 v254, 0xda24260, v254
	v_max_f32_e32 v255, 0xda24260, v255
	v_rcp_f32_e32 v248, v248
	v_rcp_f32_e32 v249, v249
	v_rcp_f32_e32 v250, v250
	v_rcp_f32_e32 v251, v251
	v_rcp_f32_e32 v252, v252
	v_rcp_f32_e32 v253, v253
	v_rcp_f32_e32 v254, v254
	v_rcp_f32_e32 v255, v255
	s_nop 0
	v_pk_mul_f32 v[158:159], v[248:249], v[158:159]
	v_pk_mul_f32 v[160:161], v[250:251], v[160:161]
	v_pk_mul_f32 v[162:163], v[252:253], v[162:163]
	v_pk_mul_f32 v[232:233], v[254:255], v[232:233]
	v_pk_mul_f32 v[58:59], v[58:59], v[158:159]
	v_pk_mul_f32 v[60:61], v[60:61], v[160:161]
	v_pk_mul_f32 v[54:55], v[54:55], v[162:163]
	v_pk_mul_f32 v[56:57], v[56:57], v[232:233]
	s_waitcnt vmcnt(10)
	v_lshlrev_b32_e32 v248, 16, v212
	v_and_b32_e32 v249, 0xffff0000, v212
	v_lshlrev_b32_e32 v250, 16, v213
	v_and_b32_e32 v251, 0xffff0000, v213
	v_lshlrev_b32_e32 v252, 16, v214
	v_and_b32_e32 v253, 0xffff0000, v214
	v_lshlrev_b32_e32 v254, 16, v215
	v_and_b32_e32 v255, 0xffff0000, v215
	v_lshlrev_b32_e32 v158, 16, v208
	v_and_b32_e32 v159, 0xffff0000, v208
	v_lshlrev_b32_e32 v160, 16, v209
	v_and_b32_e32 v161, 0xffff0000, v209
	v_lshlrev_b32_e32 v162, 16, v210
	v_and_b32_e32 v163, 0xffff0000, v210
	v_lshlrev_b32_e32 v232, 16, v211
	v_and_b32_e32 v233, 0xffff0000, v211
	v_max_f32_e32 v248, 0xda24260, v248
	v_max_f32_e32 v249, 0xda24260, v249
	v_max_f32_e32 v250, 0xda24260, v250
	v_max_f32_e32 v251, 0xda24260, v251
	v_max_f32_e32 v252, 0xda24260, v252
	v_max_f32_e32 v253, 0xda24260, v253
	v_max_f32_e32 v254, 0xda24260, v254
	v_max_f32_e32 v255, 0xda24260, v255
	v_rcp_f32_e32 v248, v248
	v_rcp_f32_e32 v249, v249
	v_rcp_f32_e32 v250, v250
	v_rcp_f32_e32 v251, v251
	v_rcp_f32_e32 v252, v252
	v_rcp_f32_e32 v253, v253
	v_rcp_f32_e32 v254, v254
	v_rcp_f32_e32 v255, v255
	s_nop 0
	v_pk_mul_f32 v[158:159], v[248:249], v[158:159]
	v_pk_mul_f32 v[160:161], v[250:251], v[160:161]
	v_pk_mul_f32 v[162:163], v[252:253], v[162:163]
	v_pk_mul_f32 v[232:233], v[254:255], v[232:233]
	v_pk_mul_f32 v[50:51], v[50:51], v[158:159]
	v_pk_mul_f32 v[52:53], v[52:53], v[160:161]
	v_pk_mul_f32 v[46:47], v[46:47], v[162:163]
	v_pk_mul_f32 v[48:49], v[48:49], v[232:233]
	s_waitcnt vmcnt(8)
	v_lshlrev_b32_e32 v248, 16, v220
	v_and_b32_e32 v249, 0xffff0000, v220
	v_lshlrev_b32_e32 v250, 16, v221
	v_and_b32_e32 v251, 0xffff0000, v221
	v_lshlrev_b32_e32 v252, 16, v222
	v_and_b32_e32 v253, 0xffff0000, v222
	v_lshlrev_b32_e32 v254, 16, v223
	v_and_b32_e32 v255, 0xffff0000, v223
	v_lshlrev_b32_e32 v158, 16, v216
	v_and_b32_e32 v159, 0xffff0000, v216
	v_lshlrev_b32_e32 v160, 16, v217
	v_and_b32_e32 v161, 0xffff0000, v217
	v_lshlrev_b32_e32 v162, 16, v218
	v_and_b32_e32 v163, 0xffff0000, v218
	v_lshlrev_b32_e32 v232, 16, v219
	v_and_b32_e32 v233, 0xffff0000, v219
	v_max_f32_e32 v248, 0xda24260, v248
	v_max_f32_e32 v249, 0xda24260, v249
	v_max_f32_e32 v250, 0xda24260, v250
	v_max_f32_e32 v251, 0xda24260, v251
	v_max_f32_e32 v252, 0xda24260, v252
	v_max_f32_e32 v253, 0xda24260, v253
	v_max_f32_e32 v254, 0xda24260, v254
	v_max_f32_e32 v255, 0xda24260, v255
	v_rcp_f32_e32 v248, v248
	v_rcp_f32_e32 v249, v249
	v_rcp_f32_e32 v250, v250
	v_rcp_f32_e32 v251, v251
	v_rcp_f32_e32 v252, v252
	v_rcp_f32_e32 v253, v253
	v_rcp_f32_e32 v254, v254
	v_rcp_f32_e32 v255, v255
	s_nop 0
	v_pk_mul_f32 v[158:159], v[248:249], v[158:159]
	v_pk_mul_f32 v[160:161], v[250:251], v[160:161]
	v_pk_mul_f32 v[162:163], v[252:253], v[162:163]
	v_pk_mul_f32 v[232:233], v[254:255], v[232:233]
	v_pk_mul_f32 v[42:43], v[42:43], v[158:159]
	v_pk_mul_f32 v[44:45], v[44:45], v[160:161]
	v_pk_mul_f32 v[38:39], v[38:39], v[162:163]
	v_pk_mul_f32 v[40:41], v[40:41], v[232:233]
	s_waitcnt vmcnt(6)
	v_lshlrev_b32_e32 v248, 16, v228
	v_and_b32_e32 v249, 0xffff0000, v228
	v_lshlrev_b32_e32 v250, 16, v229
	v_and_b32_e32 v251, 0xffff0000, v229
	v_lshlrev_b32_e32 v252, 16, v230
	v_and_b32_e32 v253, 0xffff0000, v230
	v_lshlrev_b32_e32 v254, 16, v231
	v_and_b32_e32 v255, 0xffff0000, v231
	v_lshlrev_b32_e32 v158, 16, v224
	v_and_b32_e32 v159, 0xffff0000, v224
	v_lshlrev_b32_e32 v160, 16, v225
	v_and_b32_e32 v161, 0xffff0000, v225
	v_lshlrev_b32_e32 v162, 16, v226
	v_and_b32_e32 v163, 0xffff0000, v226
	v_lshlrev_b32_e32 v232, 16, v227
	v_and_b32_e32 v233, 0xffff0000, v227
	v_max_f32_e32 v248, 0xda24260, v248
	v_max_f32_e32 v249, 0xda24260, v249
	v_max_f32_e32 v250, 0xda24260, v250
	v_max_f32_e32 v251, 0xda24260, v251
	v_max_f32_e32 v252, 0xda24260, v252
	v_max_f32_e32 v253, 0xda24260, v253
	v_max_f32_e32 v254, 0xda24260, v254
	v_max_f32_e32 v255, 0xda24260, v255
	v_rcp_f32_e32 v248, v248
	v_rcp_f32_e32 v249, v249
	v_rcp_f32_e32 v250, v250
	v_rcp_f32_e32 v251, v251
	v_rcp_f32_e32 v252, v252
	v_rcp_f32_e32 v253, v253
	v_rcp_f32_e32 v254, v254
	v_rcp_f32_e32 v255, v255
	s_nop 0
	v_pk_mul_f32 v[158:159], v[248:249], v[158:159]
	v_pk_mul_f32 v[160:161], v[250:251], v[160:161]
	v_pk_mul_f32 v[162:163], v[252:253], v[162:163]
	v_pk_mul_f32 v[232:233], v[254:255], v[232:233]
	v_pk_mul_f32 v[34:35], v[34:35], v[158:159]
	v_pk_mul_f32 v[36:37], v[36:37], v[160:161]
	v_pk_mul_f32 v[30:31], v[30:31], v[162:163]
	v_pk_mul_f32 v[32:33], v[32:33], v[232:233]
	s_waitcnt vmcnt(4)
	v_lshlrev_b32_e32 v248, 16, v138
	v_and_b32_e32 v249, 0xffff0000, v138
	v_lshlrev_b32_e32 v250, 16, v139
	v_and_b32_e32 v251, 0xffff0000, v139
	v_lshlrev_b32_e32 v252, 16, v140
	v_and_b32_e32 v253, 0xffff0000, v140
	v_lshlrev_b32_e32 v254, 16, v141
	v_and_b32_e32 v255, 0xffff0000, v141
	v_lshlrev_b32_e32 v158, 16, v134
	v_and_b32_e32 v159, 0xffff0000, v134
	v_lshlrev_b32_e32 v160, 16, v135
	v_and_b32_e32 v161, 0xffff0000, v135
	v_lshlrev_b32_e32 v162, 16, v136
	v_and_b32_e32 v163, 0xffff0000, v136
	v_lshlrev_b32_e32 v232, 16, v137
	v_and_b32_e32 v233, 0xffff0000, v137
	v_max_f32_e32 v248, 0xda24260, v248
	v_max_f32_e32 v249, 0xda24260, v249
	v_max_f32_e32 v250, 0xda24260, v250
	v_max_f32_e32 v251, 0xda24260, v251
	v_max_f32_e32 v252, 0xda24260, v252
	v_max_f32_e32 v253, 0xda24260, v253
	v_max_f32_e32 v254, 0xda24260, v254
	v_max_f32_e32 v255, 0xda24260, v255
	v_rcp_f32_e32 v248, v248
	v_rcp_f32_e32 v249, v249
	v_rcp_f32_e32 v250, v250
	v_rcp_f32_e32 v251, v251
	v_rcp_f32_e32 v252, v252
	v_rcp_f32_e32 v253, v253
	v_rcp_f32_e32 v254, v254
	v_rcp_f32_e32 v255, v255
	s_nop 0
	v_pk_mul_f32 v[158:159], v[248:249], v[158:159]
	v_pk_mul_f32 v[160:161], v[250:251], v[160:161]
	v_pk_mul_f32 v[162:163], v[252:253], v[162:163]
	v_pk_mul_f32 v[232:233], v[254:255], v[232:233]
	v_pk_mul_f32 v[26:27], v[26:27], v[158:159]
	v_pk_mul_f32 v[28:29], v[28:29], v[160:161]
	v_pk_mul_f32 v[22:23], v[22:23], v[162:163]
	v_pk_mul_f32 v[24:25], v[24:25], v[232:233]
	s_waitcnt vmcnt(2)
	v_lshlrev_b32_e32 v248, 16, v146
	v_and_b32_e32 v249, 0xffff0000, v146
	v_lshlrev_b32_e32 v250, 16, v147
	v_and_b32_e32 v251, 0xffff0000, v147
	v_lshlrev_b32_e32 v252, 16, v148
	v_and_b32_e32 v253, 0xffff0000, v148
	v_lshlrev_b32_e32 v254, 16, v149
	v_and_b32_e32 v255, 0xffff0000, v149
	v_lshlrev_b32_e32 v158, 16, v142
	v_and_b32_e32 v159, 0xffff0000, v142
	v_lshlrev_b32_e32 v160, 16, v143
	v_and_b32_e32 v161, 0xffff0000, v143
	v_lshlrev_b32_e32 v162, 16, v144
	v_and_b32_e32 v163, 0xffff0000, v144
	v_lshlrev_b32_e32 v232, 16, v145
	v_and_b32_e32 v233, 0xffff0000, v145
	v_max_f32_e32 v248, 0xda24260, v248
	v_max_f32_e32 v249, 0xda24260, v249
	v_max_f32_e32 v250, 0xda24260, v250
	v_max_f32_e32 v251, 0xda24260, v251
	v_max_f32_e32 v252, 0xda24260, v252
	v_max_f32_e32 v253, 0xda24260, v253
	v_max_f32_e32 v254, 0xda24260, v254
	v_max_f32_e32 v255, 0xda24260, v255
	v_rcp_f32_e32 v248, v248
	v_rcp_f32_e32 v249, v249
	v_rcp_f32_e32 v250, v250
	v_rcp_f32_e32 v251, v251
	v_rcp_f32_e32 v252, v252
	v_rcp_f32_e32 v253, v253
	v_rcp_f32_e32 v254, v254
	v_rcp_f32_e32 v255, v255
	s_nop 0
	v_pk_mul_f32 v[158:159], v[248:249], v[158:159]
	v_pk_mul_f32 v[160:161], v[250:251], v[160:161]
	v_pk_mul_f32 v[162:163], v[252:253], v[162:163]
	v_pk_mul_f32 v[232:233], v[254:255], v[232:233]
	v_pk_mul_f32 v[18:19], v[18:19], v[158:159]
	v_pk_mul_f32 v[20:21], v[20:21], v[160:161]
	v_pk_mul_f32 v[14:15], v[14:15], v[162:163]
	v_pk_mul_f32 v[16:17], v[16:17], v[232:233]
	s_waitcnt vmcnt(0)
	v_lshlrev_b32_e32 v248, 16, v154
	v_and_b32_e32 v249, 0xffff0000, v154
	v_lshlrev_b32_e32 v250, 16, v155
	v_and_b32_e32 v251, 0xffff0000, v155
	v_lshlrev_b32_e32 v252, 16, v156
	v_and_b32_e32 v253, 0xffff0000, v156
	v_lshlrev_b32_e32 v254, 16, v157
	v_and_b32_e32 v255, 0xffff0000, v157
	v_lshlrev_b32_e32 v158, 16, v150
	v_and_b32_e32 v159, 0xffff0000, v150
	v_lshlrev_b32_e32 v160, 16, v151
	v_and_b32_e32 v161, 0xffff0000, v151
	v_lshlrev_b32_e32 v162, 16, v152
	v_and_b32_e32 v163, 0xffff0000, v152
	v_lshlrev_b32_e32 v232, 16, v153
	v_and_b32_e32 v233, 0xffff0000, v153
	v_max_f32_e32 v248, 0xda24260, v248
	v_max_f32_e32 v249, 0xda24260, v249
	v_max_f32_e32 v250, 0xda24260, v250
	v_max_f32_e32 v251, 0xda24260, v251
	v_max_f32_e32 v252, 0xda24260, v252
	v_max_f32_e32 v253, 0xda24260, v253
	v_max_f32_e32 v254, 0xda24260, v254
	v_max_f32_e32 v255, 0xda24260, v255
	v_rcp_f32_e32 v248, v248
	v_rcp_f32_e32 v249, v249
	v_rcp_f32_e32 v250, v250
	v_rcp_f32_e32 v251, v251
	v_rcp_f32_e32 v252, v252
	v_rcp_f32_e32 v253, v253
	v_rcp_f32_e32 v254, v254
	v_rcp_f32_e32 v255, v255
	s_nop 0
	v_pk_mul_f32 v[158:159], v[248:249], v[158:159]
	v_pk_mul_f32 v[160:161], v[250:251], v[160:161]
	v_pk_mul_f32 v[162:163], v[252:253], v[162:163]
	v_pk_mul_f32 v[232:233], v[254:255], v[232:233]
	v_pk_mul_f32 v[10:11], v[10:11], v[158:159]
	v_pk_mul_f32 v[12:13], v[12:13], v[160:161]
	v_pk_mul_f32 v[6:7], v[6:7], v[162:163]
	v_pk_mul_f32 v[8:9], v[8:9], v[232:233]
	s_branch .LBB0_623
